# one precomputed scalar flag replaces the diagonal test and the max-path test on the chain between the QK MFMAs and the exps (tests moved to a side block)
# speedup vs baseline: 1.0037x; 1.0037x over previous
.Lat_entry:
	s_mov_b32 s92, m0
	s_add_i32 s71, s97, 0x8000
	s_movk_i32 s81, 0x7f
	s_mov_b32 s80, 0x20000
	s_cmp_lg_u64 s[0:1], 0
	s_mov_b32 s100, 0x8000
	s_cselect_b32 s100, 0x80000, s100
	s_add_i32 s51, s90, s100
	s_add_u32 s50, s62, s51
	s_addc_u32 s51, s63, 0
	s_mov_b32 s84, 1
	s_mov_b32 s86, 1
	s_mov_b32 s94, 0xff800000
	v_mov_b32_e32 v246, 0
	v_mov_b32_e32 v247, 0
	v_mov_b32_e32 v248, 0
	v_mov_b32_e32 v249, 0
	v_mov_b32_e32 v250, 0
	v_mov_b32_e32 v251, 0
	v_mov_b32_e32 v252, 0
	v_mov_b32_e32 v253, 0
	v_readlane_b32 s4, v254, 24
	v_and_b32_e32 v234, 15, v211
	v_lshrrev_b32_e32 v235, 4, v211
	v_xor_b32_e32 v236, v234, v235
	v_lshlrev_b32_e32 v236, 4, v236
	v_lshl_add_u32 v236, v234, 8, v236
	v_add_u32_e32 v221, s4, v236
	v_lshlrev_b32_e32 v237, 2, v235
	v_sub_u32_e32 v237, v234, v237
	v_add_u32_e32 v223, s3, v237
	v_bfe_u32 v237, v211, 5, 1
	v_lshlrev_b32_e32 v237, 12, v237
	v_bfe_u32 v238, v211, 4, 1
	v_lshl_add_u32 v237, v238, 7, v237
	v_bfe_u32 v238, v211, 2, 2
	v_lshl_add_u32 v237, v238, 5, v237
	v_and_b32_e32 v238, 3, v211
	v_lshl_add_u32 v237, v238, 3, v237
	v_bfe_u32 v237, v211, 1, 3
	v_xor_b32_e32 v237, v235, v237
	v_lshlrev_b32_e32 v237, 4, v237
	v_lshl_add_u32 v237, v234, 7, v237
	v_add_u32_e32 v242, 0x10000, v237
	v_xor_b32_e32 v243, 64, v242
	v_mov_b32_e32 v244, 0
	v_mov_b32_e32 v234, v221
	v_xor_b32_e32 v235, 64, v234
	v_xor_b32_e32 v236, 0x80, v234
	v_xor_b32_e32 v237, 0xc0, v234
	s_lshl_b64 s[98:99], s[82:83], 1
	s_add_u32 s98, s48, s98
	s_addc_u32 s99, s49, s99
	v_readlane_b32 s4, v254, 27
	s_nop 1
	v_add_u32_e32 v245, s4, v218
	v_add_u32_e32 v245, s3, v245
	v_lshlrev_b32_e32 v245, 13, v245
	v_lshl_add_u32 v245, v217, 4, v245

.Lat_dt_a:
	s_cmp_lg_u32 s86, 0
	s_cbranch_scc1 .Lat_sp_a

.Lat_redo_a:
	s_mov_b32 s84, 1
	s_mov_b32 s86, 1
	s_waitcnt lgkmcnt(0)
	v_mov_b32_e32 v234, v221
	v_xor_b32_e32 v235, 64, v234
	v_xor_b32_e32 v236, 0x80, v234
	v_xor_b32_e32 v237, 0xc0, v234
	ds_read_b128 v[162:165], v234
	s_waitcnt lgkmcnt(0)
	v_mfma_f32_16x16x32_bf16 v[130:133], v[162:165], v[178:181], v[246:249]
	v_mfma_f32_16x16x32_bf16 v[146:149], v[162:165], v[194:197], v[250:253]
	ds_read_b128 v[162:165], v235
	s_waitcnt lgkmcnt(0)
	v_mfma_f32_16x16x32_bf16 v[130:133], v[162:165], v[182:185], v[130:133]
	v_mfma_f32_16x16x32_bf16 v[146:149], v[162:165], v[198:201], v[146:149]
	ds_read_b128 v[162:165], v236
	s_waitcnt lgkmcnt(0)
	v_mfma_f32_16x16x32_bf16 v[130:133], v[162:165], v[186:189], v[130:133]
	v_mfma_f32_16x16x32_bf16 v[146:149], v[162:165], v[202:205], v[146:149]
	ds_read_b128 v[162:165], v237
	s_waitcnt lgkmcnt(0)
	v_mfma_f32_16x16x32_bf16 v[130:133], v[162:165], v[190:193], v[130:133]
	v_mfma_f32_16x16x32_bf16 v[146:149], v[162:165], v[206:209], v[146:149]
	ds_read_b128 v[162:165], v234 offset:4096
	s_waitcnt lgkmcnt(0)
	v_mfma_f32_16x16x32_bf16 v[134:137], v[162:165], v[178:181], v[246:249]
	v_mfma_f32_16x16x32_bf16 v[150:153], v[162:165], v[194:197], v[250:253]
	ds_read_b128 v[162:165], v235 offset:4096
	s_waitcnt lgkmcnt(0)
	v_mfma_f32_16x16x32_bf16 v[134:137], v[162:165], v[182:185], v[134:137]
	v_mfma_f32_16x16x32_bf16 v[150:153], v[162:165], v[198:201], v[150:153]
	ds_read_b128 v[162:165], v236 offset:4096
	s_waitcnt lgkmcnt(0)
	v_mfma_f32_16x16x32_bf16 v[134:137], v[162:165], v[186:189], v[134:137]
	v_mfma_f32_16x16x32_bf16 v[150:153], v[162:165], v[202:205], v[150:153]
	ds_read_b128 v[162:165], v237 offset:4096
	s_waitcnt lgkmcnt(0)
	v_mfma_f32_16x16x32_bf16 v[134:137], v[162:165], v[190:193], v[134:137]
	v_mfma_f32_16x16x32_bf16 v[150:153], v[162:165], v[206:209], v[150:153]
	ds_read_b128 v[162:165], v234 offset:8192
	s_waitcnt lgkmcnt(0)
	v_mfma_f32_16x16x32_bf16 v[138:141], v[162:165], v[178:181], v[246:249]
	v_mfma_f32_16x16x32_bf16 v[154:157], v[162:165], v[194:197], v[250:253]
	ds_read_b128 v[162:165], v235 offset:8192
	s_waitcnt lgkmcnt(0)
	v_mfma_f32_16x16x32_bf16 v[138:141], v[162:165], v[182:185], v[138:141]
	v_mfma_f32_16x16x32_bf16 v[154:157], v[162:165], v[198:201], v[154:157]
	ds_read_b128 v[162:165], v236 offset:8192
	s_waitcnt lgkmcnt(0)
	v_mfma_f32_16x16x32_bf16 v[138:141], v[162:165], v[186:189], v[138:141]
	v_mfma_f32_16x16x32_bf16 v[154:157], v[162:165], v[202:205], v[154:157]
	ds_read_b128 v[162:165], v237 offset:8192
	s_waitcnt lgkmcnt(0)
	v_mfma_f32_16x16x32_bf16 v[138:141], v[162:165], v[190:193], v[138:141]
	v_mfma_f32_16x16x32_bf16 v[154:157], v[162:165], v[206:209], v[154:157]
	ds_read_b128 v[162:165], v234 offset:12288
	s_waitcnt lgkmcnt(0)
	v_mfma_f32_16x16x32_bf16 v[142:145], v[162:165], v[178:181], v[246:249]
	v_mfma_f32_16x16x32_bf16 v[158:161], v[162:165], v[194:197], v[250:253]
	ds_read_b128 v[162:165], v235 offset:12288
	s_waitcnt lgkmcnt(0)
	v_mfma_f32_16x16x32_bf16 v[142:145], v[162:165], v[182:185], v[142:145]
	v_mfma_f32_16x16x32_bf16 v[158:161], v[162:165], v[198:201], v[158:161]
	ds_read_b128 v[162:165], v236 offset:12288
	s_waitcnt lgkmcnt(0)
	v_mfma_f32_16x16x32_bf16 v[142:145], v[162:165], v[186:189], v[142:145]
	v_mfma_f32_16x16x32_bf16 v[158:161], v[162:165], v[202:205], v[158:161]
	ds_read_b128 v[162:165], v237 offset:12288
	s_waitcnt lgkmcnt(0)
	v_mfma_f32_16x16x32_bf16 v[142:145], v[162:165], v[190:193], v[142:145]
	v_mfma_f32_16x16x32_bf16 v[158:161], v[162:165], v[206:209], v[158:161]
	ds_read_b128 v[162:165], v242
	ds_read_b128 v[166:169], v243
	ds_read_b128 v[170:173], v242 offset:2048
	ds_read_b128 v[174:177], v243 offset:2048
	s_nop 7
	s_branch .Lat_dt_a

.Lat_diag_a:
	s_nop 7
	v_subrev_u32_e32 v234, 0, v223
	v_cmp_gt_i32_e64 s[4:5], 0, v234
	v_med3_i32 v234, v234, 0, s81
	v_lshl_add_u32 v234, v234, 2, s80
	ds_read_b32 v238, v234
	v_subrev_u32_e32 v235, 1, v223
	v_cmp_gt_i32_e64 s[6:7], 0, v235
	v_med3_i32 v235, v235, 0, s81
	v_lshl_add_u32 v235, v235, 2, s80
	ds_read_b32 v239, v235
	v_subrev_u32_e32 v236, 2, v223
	v_cmp_gt_i32_e64 s[8:9], 0, v236
	v_med3_i32 v236, v236, 0, s81
	v_lshl_add_u32 v236, v236, 2, s80
	ds_read_b32 v240, v236
	v_subrev_u32_e32 v237, 3, v223
	v_cmp_gt_i32_e64 s[10:11], 0, v237
	v_med3_i32 v237, v237, 0, s81
	v_lshl_add_u32 v237, v237, 2, s80
	ds_read_b32 v241, v237
	s_waitcnt lgkmcnt(0)
	v_add_f32_e32 v130, v130, v238
	v_cndmask_b32_e64 v130, v130, v216, s[4:5]
	v_add_f32_e32 v131, v131, v239
	v_cndmask_b32_e64 v131, v131, v216, s[6:7]
	v_add_f32_e32 v132, v132, v240
	v_cndmask_b32_e64 v132, v132, v216, s[8:9]
	v_add_f32_e32 v133, v133, v241
	v_cndmask_b32_e64 v133, v133, v216, s[10:11]
	v_subrev_u32_e32 v234, 16, v223
	v_cmp_gt_i32_e64 s[4:5], 0, v234
	v_med3_i32 v234, v234, 0, s81
	v_lshl_add_u32 v234, v234, 2, s80
	ds_read_b32 v238, v234
	v_subrev_u32_e32 v235, 17, v223
	v_cmp_gt_i32_e64 s[6:7], 0, v235
	v_med3_i32 v235, v235, 0, s81
	v_lshl_add_u32 v235, v235, 2, s80
	ds_read_b32 v239, v235
	v_subrev_u32_e32 v236, 18, v223
	v_cmp_gt_i32_e64 s[8:9], 0, v236
	v_med3_i32 v236, v236, 0, s81
	v_lshl_add_u32 v236, v236, 2, s80
	ds_read_b32 v240, v236
	v_subrev_u32_e32 v237, 19, v223
	v_cmp_gt_i32_e64 s[10:11], 0, v237
	v_med3_i32 v237, v237, 0, s81
	v_lshl_add_u32 v237, v237, 2, s80
	ds_read_b32 v241, v237
	s_waitcnt lgkmcnt(0)
	v_add_f32_e32 v134, v134, v238
	v_cndmask_b32_e64 v134, v134, v216, s[4:5]
	v_add_f32_e32 v135, v135, v239
	v_cndmask_b32_e64 v135, v135, v216, s[6:7]
	v_add_f32_e32 v136, v136, v240
	v_cndmask_b32_e64 v136, v136, v216, s[8:9]
	v_add_f32_e32 v137, v137, v241
	v_cndmask_b32_e64 v137, v137, v216, s[10:11]
	v_subrev_u32_e32 v234, 32, v223
	v_cmp_gt_i32_e64 s[4:5], 0, v234
	v_med3_i32 v234, v234, 0, s81
	v_lshl_add_u32 v234, v234, 2, s80
	ds_read_b32 v238, v234
	v_subrev_u32_e32 v235, 33, v223
	v_cmp_gt_i32_e64 s[6:7], 0, v235
	v_med3_i32 v235, v235, 0, s81
	v_lshl_add_u32 v235, v235, 2, s80
	ds_read_b32 v239, v235
	v_subrev_u32_e32 v236, 34, v223
	v_cmp_gt_i32_e64 s[8:9], 0, v236
	v_med3_i32 v236, v236, 0, s81
	v_lshl_add_u32 v236, v236, 2, s80
	ds_read_b32 v240, v236
	v_subrev_u32_e32 v237, 35, v223
	v_cmp_gt_i32_e64 s[10:11], 0, v237
	v_med3_i32 v237, v237, 0, s81
	v_lshl_add_u32 v237, v237, 2, s80
	ds_read_b32 v241, v237
	s_waitcnt lgkmcnt(0)
	v_add_f32_e32 v138, v138, v238
	v_cndmask_b32_e64 v138, v138, v216, s[4:5]
	v_add_f32_e32 v139, v139, v239
	v_cndmask_b32_e64 v139, v139, v216, s[6:7]
	v_add_f32_e32 v140, v140, v240
	v_cndmask_b32_e64 v140, v140, v216, s[8:9]
	v_add_f32_e32 v141, v141, v241
	v_cndmask_b32_e64 v141, v141, v216, s[10:11]
	v_subrev_u32_e32 v234, 48, v223
	v_cmp_gt_i32_e64 s[4:5], 0, v234
	v_med3_i32 v234, v234, 0, s81
	v_lshl_add_u32 v234, v234, 2, s80
	ds_read_b32 v238, v234
	v_subrev_u32_e32 v235, 49, v223
	v_cmp_gt_i32_e64 s[6:7], 0, v235
	v_med3_i32 v235, v235, 0, s81
	v_lshl_add_u32 v235, v235, 2, s80
	ds_read_b32 v239, v235
	v_subrev_u32_e32 v236, 50, v223
	v_cmp_gt_i32_e64 s[8:9], 0, v236
	v_med3_i32 v236, v236, 0, s81
	v_lshl_add_u32 v236, v236, 2, s80
	ds_read_b32 v240, v236
	v_subrev_u32_e32 v237, 51, v223
	v_cmp_gt_i32_e64 s[10:11], 0, v237
	v_med3_i32 v237, v237, 0, s81
	v_lshl_add_u32 v237, v237, 2, s80
	ds_read_b32 v241, v237
	s_waitcnt lgkmcnt(0)
	v_add_f32_e32 v142, v142, v238
	v_cndmask_b32_e64 v142, v142, v216, s[4:5]
	v_add_f32_e32 v143, v143, v239
	v_cndmask_b32_e64 v143, v143, v216, s[6:7]
	v_add_f32_e32 v144, v144, v240
	v_cndmask_b32_e64 v144, v144, v216, s[8:9]
	v_add_f32_e32 v145, v145, v241
	v_cndmask_b32_e64 v145, v145, v216, s[10:11]
	v_subrev_u32_e32 v234, -16, v223
	v_cmp_gt_i32_e64 s[4:5], 0, v234
	v_med3_i32 v234, v234, 0, s81
	v_lshl_add_u32 v234, v234, 2, s80
	ds_read_b32 v238, v234
	v_subrev_u32_e32 v235, -15, v223
	v_cmp_gt_i32_e64 s[6:7], 0, v235
	v_med3_i32 v235, v235, 0, s81
	v_lshl_add_u32 v235, v235, 2, s80
	ds_read_b32 v239, v235
	v_subrev_u32_e32 v236, -14, v223
	v_cmp_gt_i32_e64 s[8:9], 0, v236
	v_med3_i32 v236, v236, 0, s81
	v_lshl_add_u32 v236, v236, 2, s80
	ds_read_b32 v240, v236
	v_subrev_u32_e32 v237, -13, v223
	v_cmp_gt_i32_e64 s[10:11], 0, v237
	v_med3_i32 v237, v237, 0, s81
	v_lshl_add_u32 v237, v237, 2, s80
	ds_read_b32 v241, v237
	s_waitcnt lgkmcnt(0)
	v_add_f32_e32 v146, v146, v238
	v_cndmask_b32_e64 v146, v146, v216, s[4:5]
	v_add_f32_e32 v147, v147, v239
	v_cndmask_b32_e64 v147, v147, v216, s[6:7]
	v_add_f32_e32 v148, v148, v240
	v_cndmask_b32_e64 v148, v148, v216, s[8:9]
	v_add_f32_e32 v149, v149, v241
	v_cndmask_b32_e64 v149, v149, v216, s[10:11]
	v_subrev_u32_e32 v234, 0, v223
	v_cmp_gt_i32_e64 s[4:5], 0, v234
	v_med3_i32 v234, v234, 0, s81
	v_lshl_add_u32 v234, v234, 2, s80
	ds_read_b32 v238, v234
	v_subrev_u32_e32 v235, 1, v223
	v_cmp_gt_i32_e64 s[6:7], 0, v235
	v_med3_i32 v235, v235, 0, s81
	v_lshl_add_u32 v235, v235, 2, s80
	ds_read_b32 v239, v235
	v_subrev_u32_e32 v236, 2, v223
	v_cmp_gt_i32_e64 s[8:9], 0, v236
	v_med3_i32 v236, v236, 0, s81
	v_lshl_add_u32 v236, v236, 2, s80
	ds_read_b32 v240, v236
	v_subrev_u32_e32 v237, 3, v223
	v_cmp_gt_i32_e64 s[10:11], 0, v237
	v_med3_i32 v237, v237, 0, s81
	v_lshl_add_u32 v237, v237, 2, s80
	ds_read_b32 v241, v237
	s_waitcnt lgkmcnt(0)
	v_add_f32_e32 v150, v150, v238
	v_cndmask_b32_e64 v150, v150, v216, s[4:5]
	v_add_f32_e32 v151, v151, v239
	v_cndmask_b32_e64 v151, v151, v216, s[6:7]
	v_add_f32_e32 v152, v152, v240
	v_cndmask_b32_e64 v152, v152, v216, s[8:9]
	v_add_f32_e32 v153, v153, v241
	v_cndmask_b32_e64 v153, v153, v216, s[10:11]
	v_subrev_u32_e32 v234, 16, v223
	v_cmp_gt_i32_e64 s[4:5], 0, v234
	v_med3_i32 v234, v234, 0, s81
	v_lshl_add_u32 v234, v234, 2, s80
	ds_read_b32 v238, v234
	v_subrev_u32_e32 v235, 17, v223
	v_cmp_gt_i32_e64 s[6:7], 0, v235
	v_med3_i32 v235, v235, 0, s81
	v_lshl_add_u32 v235, v235, 2, s80
	ds_read_b32 v239, v235
	v_subrev_u32_e32 v236, 18, v223
	v_cmp_gt_i32_e64 s[8:9], 0, v236
	v_med3_i32 v236, v236, 0, s81
	v_lshl_add_u32 v236, v236, 2, s80
	ds_read_b32 v240, v236
	v_subrev_u32_e32 v237, 19, v223
	v_cmp_gt_i32_e64 s[10:11], 0, v237
	v_med3_i32 v237, v237, 0, s81
	v_lshl_add_u32 v237, v237, 2, s80
	ds_read_b32 v241, v237
	s_waitcnt lgkmcnt(0)
	v_add_f32_e32 v154, v154, v238
	v_cndmask_b32_e64 v154, v154, v216, s[4:5]
	v_add_f32_e32 v155, v155, v239
	v_cndmask_b32_e64 v155, v155, v216, s[6:7]
	v_add_f32_e32 v156, v156, v240
	v_cndmask_b32_e64 v156, v156, v216, s[8:9]
	v_add_f32_e32 v157, v157, v241
	v_cndmask_b32_e64 v157, v157, v216, s[10:11]
	v_subrev_u32_e32 v234, 32, v223
	v_cmp_gt_i32_e64 s[4:5], 0, v234
	v_med3_i32 v234, v234, 0, s81
	v_lshl_add_u32 v234, v234, 2, s80
	ds_read_b32 v238, v234
	v_subrev_u32_e32 v235, 33, v223
	v_cmp_gt_i32_e64 s[6:7], 0, v235
	v_med3_i32 v235, v235, 0, s81
	v_lshl_add_u32 v235, v235, 2, s80
	ds_read_b32 v239, v235
	v_subrev_u32_e32 v236, 34, v223
	v_cmp_gt_i32_e64 s[8:9], 0, v236
	v_med3_i32 v236, v236, 0, s81
	v_lshl_add_u32 v236, v236, 2, s80
	ds_read_b32 v240, v236
	v_subrev_u32_e32 v237, 35, v223
	v_cmp_gt_i32_e64 s[10:11], 0, v237
	v_med3_i32 v237, v237, 0, s81
	v_lshl_add_u32 v237, v237, 2, s80
	ds_read_b32 v241, v237
	s_waitcnt lgkmcnt(0)
	v_add_f32_e32 v158, v158, v238
	v_cndmask_b32_e64 v158, v158, v216, s[4:5]
	v_add_f32_e32 v159, v159, v239
	v_cndmask_b32_e64 v159, v159, v216, s[6:7]
	v_add_f32_e32 v160, v160, v240
	v_cndmask_b32_e64 v160, v160, v216, s[8:9]
	v_add_f32_e32 v161, v161, v241
	v_cndmask_b32_e64 v161, v161, v216, s[10:11]
	v_mov_b32_e32 v234, v221
	v_xor_b32_e32 v235, 64, v234
	v_xor_b32_e32 v236, 0x80, v234
	v_xor_b32_e32 v237, 0xc0, v234
	s_branch .Lat_sm_a
.Lat_sp_a:
	s_add_i32 s4, s91, 0xb0
	s_cmp_le_u32 s4, s3
	s_cbranch_scc0 .Lat_diag_a
.Lat_sm_a:
	s_cmp_lg_u32 s84, 0
	s_cbranch_scc1 .Lat_max_a
	s_branch .Lat_exp_a
.Lat_end_a:
.Lat_next0:
	s_add_i32 s58, s58, 1
	v_add_u32_e32 v223, 0xffffffc0, v223
	s_addk_i32 s91, 0x40
	s_add_u32 s50, s50, s100
	s_addc_u32 s51, s51, 0
	s_mov_b32 s94, 0
	s_add_i32 s4, s91, 0xb0
	s_cmp_gt_u32 s4, s3
	s_cselect_b32 s86, 1, 0
	s_or_b32 s86, s86, s84
	s_cmp_gt_u32 s58, s88
	s_cbranch_scc1 .Lat_final
	s_waitcnt vmcnt(0) lgkmcnt(0)
	s_barrier
	s_cmp_gt_u32 s58, s89
	s_cbranch_scc1 .Lat_inactive1
	ds_read_b128 v[162:165], v234 offset:32768
	ds_read_b128 v[166:169], v235 offset:32768
	ds_read_b128 v[170:173], v236 offset:32768
	ds_read_b128 v[174:177], v237 offset:32768
	s_waitcnt lgkmcnt(2)
	v_mfma_f32_16x16x32_bf16 v[130:133], v[162:165], v[178:181], v[246:249]
	s_add_i32 m0, s97, 0x0
	v_mfma_f32_16x16x32_bf16 v[146:149], v[162:165], v[194:197], v[250:253]
	ds_read_b128 v[162:165], v234 offset:36864
	global_load_lds_dwordx4 v231, s[50:51]
	v_mfma_f32_16x16x32_bf16 v[130:133], v[166:169], v[182:185], v[130:133]
	v_mfma_f32_16x16x32_bf16 v[146:149], v[166:169], v[198:201], v[146:149]
	ds_read_b128 v[166:169], v235 offset:36864
	s_waitcnt lgkmcnt(2)
	v_mfma_f32_16x16x32_bf16 v[130:133], v[170:173], v[186:189], v[130:133]
	s_add_i32 m0, s97, 0x400
	v_mfma_f32_16x16x32_bf16 v[146:149], v[170:173], v[202:205], v[146:149]
	ds_read_b128 v[170:173], v236 offset:36864
	global_load_lds_dwordx4 v229, s[50:51]
	v_mfma_f32_16x16x32_bf16 v[130:133], v[174:177], v[190:193], v[130:133]
	v_mfma_f32_16x16x32_bf16 v[146:149], v[174:177], v[206:209], v[146:149]
	ds_read_b128 v[174:177], v237 offset:36864
	s_waitcnt lgkmcnt(2)
	v_mfma_f32_16x16x32_bf16 v[134:137], v[162:165], v[178:181], v[246:249]
	s_add_i32 m0, s97, 0x800
	v_mfma_f32_16x16x32_bf16 v[150:153], v[162:165], v[194:197], v[250:253]
	ds_read_b128 v[162:165], v234 offset:40960
	global_load_lds_dwordx4 v227, s[50:51]
	v_mfma_f32_16x16x32_bf16 v[134:137], v[166:169], v[182:185], v[134:137]
	v_mfma_f32_16x16x32_bf16 v[150:153], v[166:169], v[198:201], v[150:153]
	ds_read_b128 v[166:169], v235 offset:40960
	s_waitcnt lgkmcnt(2)
	v_mfma_f32_16x16x32_bf16 v[134:137], v[170:173], v[186:189], v[134:137]
	s_add_i32 m0, s97, 0xc00
	v_mfma_f32_16x16x32_bf16 v[150:153], v[170:173], v[202:205], v[150:153]
	ds_read_b128 v[170:173], v236 offset:40960
	global_load_lds_dwordx4 v225, s[50:51]
	v_mfma_f32_16x16x32_bf16 v[134:137], v[174:177], v[190:193], v[134:137]
	v_mfma_f32_16x16x32_bf16 v[150:153], v[174:177], v[206:209], v[150:153]
	ds_read_b128 v[174:177], v237 offset:40960
	s_waitcnt lgkmcnt(2)
	v_mfma_f32_16x16x32_bf16 v[138:141], v[162:165], v[178:181], v[246:249]
	s_add_i32 m0, s97, 0x1000
	v_mfma_f32_16x16x32_bf16 v[154:157], v[162:165], v[194:197], v[250:253]
	ds_read_b128 v[162:165], v234 offset:45056
	global_load_lds_dwordx4 v230, s[50:51]
	v_mfma_f32_16x16x32_bf16 v[138:141], v[166:169], v[182:185], v[138:141]
	v_mfma_f32_16x16x32_bf16 v[154:157], v[166:169], v[198:201], v[154:157]
	ds_read_b128 v[166:169], v235 offset:45056
	s_waitcnt lgkmcnt(2)
	v_mfma_f32_16x16x32_bf16 v[138:141], v[170:173], v[186:189], v[138:141]
	s_add_i32 m0, s97, 0x1400
	v_mfma_f32_16x16x32_bf16 v[154:157], v[170:173], v[202:205], v[154:157]
	ds_read_b128 v[170:173], v236 offset:45056
	global_load_lds_dwordx4 v228, s[50:51]
	v_mfma_f32_16x16x32_bf16 v[138:141], v[174:177], v[190:193], v[138:141]
	v_mfma_f32_16x16x32_bf16 v[154:157], v[174:177], v[206:209], v[154:157]
	ds_read_b128 v[174:177], v237 offset:45056
	s_waitcnt lgkmcnt(2)
	v_mfma_f32_16x16x32_bf16 v[142:145], v[162:165], v[178:181], v[246:249]
	s_add_i32 m0, s97, 0x1800
	v_mfma_f32_16x16x32_bf16 v[158:161], v[162:165], v[194:197], v[250:253]
	ds_read_b128 v[162:165], v242 offset:32768
	global_load_lds_dwordx4 v226, s[50:51]
	v_mfma_f32_16x16x32_bf16 v[142:145], v[166:169], v[182:185], v[142:145]
	v_mfma_f32_16x16x32_bf16 v[158:161], v[166:169], v[198:201], v[158:161]
	ds_read_b128 v[166:169], v243 offset:32768
	s_waitcnt lgkmcnt(2)
	v_mfma_f32_16x16x32_bf16 v[142:145], v[170:173], v[186:189], v[142:145]
	s_add_i32 m0, s97, 0x1c00
	v_mfma_f32_16x16x32_bf16 v[158:161], v[170:173], v[202:205], v[158:161]
	ds_read_b128 v[170:173], v242 offset:34816
	global_load_lds_dwordx4 v224, s[50:51]
	v_mfma_f32_16x16x32_bf16 v[142:145], v[174:177], v[190:193], v[142:145]
	v_mfma_f32_16x16x32_bf16 v[158:161], v[174:177], v[206:209], v[158:161]
	ds_read_b128 v[174:177], v243 offset:34816

.Lat_redo_c:
	s_mov_b32 s84, 1
	s_mov_b32 s86, 1
	s_waitcnt lgkmcnt(0)
	v_mov_b32_e32 v234, v221
	v_xor_b32_e32 v235, 64, v234
	v_xor_b32_e32 v236, 0x80, v234
	v_xor_b32_e32 v237, 0xc0, v234
	ds_read_b128 v[162:165], v234 offset:32768
	s_waitcnt lgkmcnt(0)
	v_mfma_f32_16x16x32_bf16 v[130:133], v[162:165], v[178:181], v[246:249]
	v_mfma_f32_16x16x32_bf16 v[146:149], v[162:165], v[194:197], v[250:253]
	ds_read_b128 v[162:165], v235 offset:32768
	s_waitcnt lgkmcnt(0)
	v_mfma_f32_16x16x32_bf16 v[130:133], v[162:165], v[182:185], v[130:133]
	v_mfma_f32_16x16x32_bf16 v[146:149], v[162:165], v[198:201], v[146:149]
	ds_read_b128 v[162:165], v236 offset:32768
	s_waitcnt lgkmcnt(0)
	v_mfma_f32_16x16x32_bf16 v[130:133], v[162:165], v[186:189], v[130:133]
	v_mfma_f32_16x16x32_bf16 v[146:149], v[162:165], v[202:205], v[146:149]
	ds_read_b128 v[162:165], v237 offset:32768
	s_waitcnt lgkmcnt(0)
	v_mfma_f32_16x16x32_bf16 v[130:133], v[162:165], v[190:193], v[130:133]
	v_mfma_f32_16x16x32_bf16 v[146:149], v[162:165], v[206:209], v[146:149]
	ds_read_b128 v[162:165], v234 offset:36864
	s_waitcnt lgkmcnt(0)
	v_mfma_f32_16x16x32_bf16 v[134:137], v[162:165], v[178:181], v[246:249]
	v_mfma_f32_16x16x32_bf16 v[150:153], v[162:165], v[194:197], v[250:253]
	ds_read_b128 v[162:165], v235 offset:36864
	s_waitcnt lgkmcnt(0)
	v_mfma_f32_16x16x32_bf16 v[134:137], v[162:165], v[182:185], v[134:137]
	v_mfma_f32_16x16x32_bf16 v[150:153], v[162:165], v[198:201], v[150:153]
	ds_read_b128 v[162:165], v236 offset:36864
	s_waitcnt lgkmcnt(0)
	v_mfma_f32_16x16x32_bf16 v[134:137], v[162:165], v[186:189], v[134:137]
	v_mfma_f32_16x16x32_bf16 v[150:153], v[162:165], v[202:205], v[150:153]
	ds_read_b128 v[162:165], v237 offset:36864
	s_waitcnt lgkmcnt(0)
	v_mfma_f32_16x16x32_bf16 v[134:137], v[162:165], v[190:193], v[134:137]
	v_mfma_f32_16x16x32_bf16 v[150:153], v[162:165], v[206:209], v[150:153]
	ds_read_b128 v[162:165], v234 offset:40960
	s_waitcnt lgkmcnt(0)
	v_mfma_f32_16x16x32_bf16 v[138:141], v[162:165], v[178:181], v[246:249]
	v_mfma_f32_16x16x32_bf16 v[154:157], v[162:165], v[194:197], v[250:253]
	ds_read_b128 v[162:165], v235 offset:40960
	s_waitcnt lgkmcnt(0)
	v_mfma_f32_16x16x32_bf16 v[138:141], v[162:165], v[182:185], v[138:141]
	v_mfma_f32_16x16x32_bf16 v[154:157], v[162:165], v[198:201], v[154:157]
	ds_read_b128 v[162:165], v236 offset:40960
	s_waitcnt lgkmcnt(0)
	v_mfma_f32_16x16x32_bf16 v[138:141], v[162:165], v[186:189], v[138:141]
	v_mfma_f32_16x16x32_bf16 v[154:157], v[162:165], v[202:205], v[154:157]
	ds_read_b128 v[162:165], v237 offset:40960
	s_waitcnt lgkmcnt(0)
	v_mfma_f32_16x16x32_bf16 v[138:141], v[162:165], v[190:193], v[138:141]
	v_mfma_f32_16x16x32_bf16 v[154:157], v[162:165], v[206:209], v[154:157]
	ds_read_b128 v[162:165], v234 offset:45056
	s_waitcnt lgkmcnt(0)
	v_mfma_f32_16x16x32_bf16 v[142:145], v[162:165], v[178:181], v[246:249]
	v_mfma_f32_16x16x32_bf16 v[158:161], v[162:165], v[194:197], v[250:253]
	ds_read_b128 v[162:165], v235 offset:45056
	s_waitcnt lgkmcnt(0)
	v_mfma_f32_16x16x32_bf16 v[142:145], v[162:165], v[182:185], v[142:145]
	v_mfma_f32_16x16x32_bf16 v[158:161], v[162:165], v[198:201], v[158:161]
	ds_read_b128 v[162:165], v236 offset:45056
	s_waitcnt lgkmcnt(0)
	v_mfma_f32_16x16x32_bf16 v[142:145], v[162:165], v[186:189], v[142:145]
	v_mfma_f32_16x16x32_bf16 v[158:161], v[162:165], v[202:205], v[158:161]
	ds_read_b128 v[162:165], v237 offset:45056
	s_waitcnt lgkmcnt(0)
	v_mfma_f32_16x16x32_bf16 v[142:145], v[162:165], v[190:193], v[142:145]
	v_mfma_f32_16x16x32_bf16 v[158:161], v[162:165], v[206:209], v[158:161]
	ds_read_b128 v[162:165], v242 offset:32768
	ds_read_b128 v[166:169], v243 offset:32768
	ds_read_b128 v[170:173], v242 offset:34816
	ds_read_b128 v[174:177], v243 offset:34816
	s_nop 7
	s_branch .Lat_dt_c

.Lat_diag_c:
	s_nop 7
	v_subrev_u32_e32 v234, 0, v223
	v_cmp_gt_i32_e64 s[4:5], 0, v234
	v_med3_i32 v234, v234, 0, s81
	v_lshl_add_u32 v234, v234, 2, s80
	ds_read_b32 v238, v234
	v_subrev_u32_e32 v235, 1, v223
	v_cmp_gt_i32_e64 s[6:7], 0, v235
	v_med3_i32 v235, v235, 0, s81
	v_lshl_add_u32 v235, v235, 2, s80
	ds_read_b32 v239, v235
	v_subrev_u32_e32 v236, 2, v223
	v_cmp_gt_i32_e64 s[8:9], 0, v236
	v_med3_i32 v236, v236, 0, s81
	v_lshl_add_u32 v236, v236, 2, s80
	ds_read_b32 v240, v236
	v_subrev_u32_e32 v237, 3, v223
	v_cmp_gt_i32_e64 s[10:11], 0, v237
	v_med3_i32 v237, v237, 0, s81
	v_lshl_add_u32 v237, v237, 2, s80
	ds_read_b32 v241, v237
	s_waitcnt lgkmcnt(0)
	v_add_f32_e32 v130, v130, v238
	v_cndmask_b32_e64 v130, v130, v216, s[4:5]
	v_add_f32_e32 v131, v131, v239
	v_cndmask_b32_e64 v131, v131, v216, s[6:7]
	v_add_f32_e32 v132, v132, v240
	v_cndmask_b32_e64 v132, v132, v216, s[8:9]
	v_add_f32_e32 v133, v133, v241
	v_cndmask_b32_e64 v133, v133, v216, s[10:11]
	v_subrev_u32_e32 v234, 16, v223
	v_cmp_gt_i32_e64 s[4:5], 0, v234
	v_med3_i32 v234, v234, 0, s81
	v_lshl_add_u32 v234, v234, 2, s80
	ds_read_b32 v238, v234
	v_subrev_u32_e32 v235, 17, v223
	v_cmp_gt_i32_e64 s[6:7], 0, v235
	v_med3_i32 v235, v235, 0, s81
	v_lshl_add_u32 v235, v235, 2, s80
	ds_read_b32 v239, v235
	v_subrev_u32_e32 v236, 18, v223
	v_cmp_gt_i32_e64 s[8:9], 0, v236
	v_med3_i32 v236, v236, 0, s81
	v_lshl_add_u32 v236, v236, 2, s80
	ds_read_b32 v240, v236
	v_subrev_u32_e32 v237, 19, v223
	v_cmp_gt_i32_e64 s[10:11], 0, v237
	v_med3_i32 v237, v237, 0, s81
	v_lshl_add_u32 v237, v237, 2, s80
	ds_read_b32 v241, v237
	s_waitcnt lgkmcnt(0)
	v_add_f32_e32 v134, v134, v238
	v_cndmask_b32_e64 v134, v134, v216, s[4:5]
	v_add_f32_e32 v135, v135, v239
	v_cndmask_b32_e64 v135, v135, v216, s[6:7]
	v_add_f32_e32 v136, v136, v240
	v_cndmask_b32_e64 v136, v136, v216, s[8:9]
	v_add_f32_e32 v137, v137, v241
	v_cndmask_b32_e64 v137, v137, v216, s[10:11]
	v_subrev_u32_e32 v234, 32, v223
	v_cmp_gt_i32_e64 s[4:5], 0, v234
	v_med3_i32 v234, v234, 0, s81
	v_lshl_add_u32 v234, v234, 2, s80
	ds_read_b32 v238, v234
	v_subrev_u32_e32 v235, 33, v223
	v_cmp_gt_i32_e64 s[6:7], 0, v235
	v_med3_i32 v235, v235, 0, s81
	v_lshl_add_u32 v235, v235, 2, s80
	ds_read_b32 v239, v235
	v_subrev_u32_e32 v236, 34, v223
	v_cmp_gt_i32_e64 s[8:9], 0, v236
	v_med3_i32 v236, v236, 0, s81
	v_lshl_add_u32 v236, v236, 2, s80
	ds_read_b32 v240, v236
	v_subrev_u32_e32 v237, 35, v223
	v_cmp_gt_i32_e64 s[10:11], 0, v237
	v_med3_i32 v237, v237, 0, s81
	v_lshl_add_u32 v237, v237, 2, s80
	ds_read_b32 v241, v237
	s_waitcnt lgkmcnt(0)
	v_add_f32_e32 v138, v138, v238
	v_cndmask_b32_e64 v138, v138, v216, s[4:5]
	v_add_f32_e32 v139, v139, v239
	v_cndmask_b32_e64 v139, v139, v216, s[6:7]
	v_add_f32_e32 v140, v140, v240
	v_cndmask_b32_e64 v140, v140, v216, s[8:9]
	v_add_f32_e32 v141, v141, v241
	v_cndmask_b32_e64 v141, v141, v216, s[10:11]
	v_subrev_u32_e32 v234, 48, v223
	v_cmp_gt_i32_e64 s[4:5], 0, v234
	v_med3_i32 v234, v234, 0, s81
	v_lshl_add_u32 v234, v234, 2, s80
	ds_read_b32 v238, v234
	v_subrev_u32_e32 v235, 49, v223
	v_cmp_gt_i32_e64 s[6:7], 0, v235
	v_med3_i32 v235, v235, 0, s81
	v_lshl_add_u32 v235, v235, 2, s80
	ds_read_b32 v239, v235
	v_subrev_u32_e32 v236, 50, v223
	v_cmp_gt_i32_e64 s[8:9], 0, v236
	v_med3_i32 v236, v236, 0, s81
	v_lshl_add_u32 v236, v236, 2, s80
	ds_read_b32 v240, v236
	v_subrev_u32_e32 v237, 51, v223
	v_cmp_gt_i32_e64 s[10:11], 0, v237
	v_med3_i32 v237, v237, 0, s81
	v_lshl_add_u32 v237, v237, 2, s80
	ds_read_b32 v241, v237
	s_waitcnt lgkmcnt(0)
	v_add_f32_e32 v142, v142, v238
	v_cndmask_b32_e64 v142, v142, v216, s[4:5]
	v_add_f32_e32 v143, v143, v239
	v_cndmask_b32_e64 v143, v143, v216, s[6:7]
	v_add_f32_e32 v144, v144, v240
	v_cndmask_b32_e64 v144, v144, v216, s[8:9]
	v_add_f32_e32 v145, v145, v241
	v_cndmask_b32_e64 v145, v145, v216, s[10:11]
	v_subrev_u32_e32 v234, -16, v223
	v_cmp_gt_i32_e64 s[4:5], 0, v234
	v_med3_i32 v234, v234, 0, s81
	v_lshl_add_u32 v234, v234, 2, s80
	ds_read_b32 v238, v234
	v_subrev_u32_e32 v235, -15, v223
	v_cmp_gt_i32_e64 s[6:7], 0, v235
	v_med3_i32 v235, v235, 0, s81
	v_lshl_add_u32 v235, v235, 2, s80
	ds_read_b32 v239, v235
	v_subrev_u32_e32 v236, -14, v223
	v_cmp_gt_i32_e64 s[8:9], 0, v236
	v_med3_i32 v236, v236, 0, s81
	v_lshl_add_u32 v236, v236, 2, s80
	ds_read_b32 v240, v236
	v_subrev_u32_e32 v237, -13, v223
	v_cmp_gt_i32_e64 s[10:11], 0, v237
	v_med3_i32 v237, v237, 0, s81
	v_lshl_add_u32 v237, v237, 2, s80
	ds_read_b32 v241, v237
	s_waitcnt lgkmcnt(0)
	v_add_f32_e32 v146, v146, v238
	v_cndmask_b32_e64 v146, v146, v216, s[4:5]
	v_add_f32_e32 v147, v147, v239
	v_cndmask_b32_e64 v147, v147, v216, s[6:7]
	v_add_f32_e32 v148, v148, v240
	v_cndmask_b32_e64 v148, v148, v216, s[8:9]
	v_add_f32_e32 v149, v149, v241
	v_cndmask_b32_e64 v149, v149, v216, s[10:11]
	v_subrev_u32_e32 v234, 0, v223
	v_cmp_gt_i32_e64 s[4:5], 0, v234
	v_med3_i32 v234, v234, 0, s81
	v_lshl_add_u32 v234, v234, 2, s80
	ds_read_b32 v238, v234
	v_subrev_u32_e32 v235, 1, v223
	v_cmp_gt_i32_e64 s[6:7], 0, v235
	v_med3_i32 v235, v235, 0, s81
	v_lshl_add_u32 v235, v235, 2, s80
	ds_read_b32 v239, v235
	v_subrev_u32_e32 v236, 2, v223
	v_cmp_gt_i32_e64 s[8:9], 0, v236
	v_med3_i32 v236, v236, 0, s81
	v_lshl_add_u32 v236, v236, 2, s80
	ds_read_b32 v240, v236
	v_subrev_u32_e32 v237, 3, v223
	v_cmp_gt_i32_e64 s[10:11], 0, v237
	v_med3_i32 v237, v237, 0, s81
	v_lshl_add_u32 v237, v237, 2, s80
	ds_read_b32 v241, v237
	s_waitcnt lgkmcnt(0)
	v_add_f32_e32 v150, v150, v238
	v_cndmask_b32_e64 v150, v150, v216, s[4:5]
	v_add_f32_e32 v151, v151, v239
	v_cndmask_b32_e64 v151, v151, v216, s[6:7]
	v_add_f32_e32 v152, v152, v240
	v_cndmask_b32_e64 v152, v152, v216, s[8:9]
	v_add_f32_e32 v153, v153, v241
	v_cndmask_b32_e64 v153, v153, v216, s[10:11]
	v_subrev_u32_e32 v234, 16, v223
	v_cmp_gt_i32_e64 s[4:5], 0, v234
	v_med3_i32 v234, v234, 0, s81
	v_lshl_add_u32 v234, v234, 2, s80
	ds_read_b32 v238, v234
	v_subrev_u32_e32 v235, 17, v223
	v_cmp_gt_i32_e64 s[6:7], 0, v235
	v_med3_i32 v235, v235, 0, s81
	v_lshl_add_u32 v235, v235, 2, s80
	ds_read_b32 v239, v235
	v_subrev_u32_e32 v236, 18, v223
	v_cmp_gt_i32_e64 s[8:9], 0, v236
	v_med3_i32 v236, v236, 0, s81
	v_lshl_add_u32 v236, v236, 2, s80
	ds_read_b32 v240, v236
	v_subrev_u32_e32 v237, 19, v223
	v_cmp_gt_i32_e64 s[10:11], 0, v237
	v_med3_i32 v237, v237, 0, s81
	v_lshl_add_u32 v237, v237, 2, s80
	ds_read_b32 v241, v237
	s_waitcnt lgkmcnt(0)
	v_add_f32_e32 v154, v154, v238
	v_cndmask_b32_e64 v154, v154, v216, s[4:5]
	v_add_f32_e32 v155, v155, v239
	v_cndmask_b32_e64 v155, v155, v216, s[6:7]
	v_add_f32_e32 v156, v156, v240
	v_cndmask_b32_e64 v156, v156, v216, s[8:9]
	v_add_f32_e32 v157, v157, v241
	v_cndmask_b32_e64 v157, v157, v216, s[10:11]
	v_subrev_u32_e32 v234, 32, v223
	v_cmp_gt_i32_e64 s[4:5], 0, v234
	v_med3_i32 v234, v234, 0, s81
	v_lshl_add_u32 v234, v234, 2, s80
	ds_read_b32 v238, v234
	v_subrev_u32_e32 v235, 33, v223
	v_cmp_gt_i32_e64 s[6:7], 0, v235
	v_med3_i32 v235, v235, 0, s81
	v_lshl_add_u32 v235, v235, 2, s80
	ds_read_b32 v239, v235
	v_subrev_u32_e32 v236, 34, v223
	v_cmp_gt_i32_e64 s[8:9], 0, v236
	v_med3_i32 v236, v236, 0, s81
	v_lshl_add_u32 v236, v236, 2, s80
	ds_read_b32 v240, v236
	v_subrev_u32_e32 v237, 35, v223
	v_cmp_gt_i32_e64 s[10:11], 0, v237
	v_med3_i32 v237, v237, 0, s81
	v_lshl_add_u32 v237, v237, 2, s80
	ds_read_b32 v241, v237
	s_waitcnt lgkmcnt(0)
	v_add_f32_e32 v158, v158, v238
	v_cndmask_b32_e64 v158, v158, v216, s[4:5]
	v_add_f32_e32 v159, v159, v239
	v_cndmask_b32_e64 v159, v159, v216, s[6:7]
	v_add_f32_e32 v160, v160, v240
	v_cndmask_b32_e64 v160, v160, v216, s[8:9]
	v_add_f32_e32 v161, v161, v241
	v_cndmask_b32_e64 v161, v161, v216, s[10:11]
	v_mov_b32_e32 v234, v221
	v_xor_b32_e32 v235, 64, v234
	v_xor_b32_e32 v236, 0x80, v234
	v_xor_b32_e32 v237, 0xc0, v234
	s_branch .Lat_sm_c
.Lat_sp_c:
	s_add_i32 s4, s91, 0xb0
	s_cmp_le_u32 s4, s3
	s_cbranch_scc0 .Lat_diag_c

.Lat_end_c:
.Lat_next1:
	s_add_i32 s58, s58, 1
	v_add_u32_e32 v223, 0xffffffc0, v223
	s_addk_i32 s91, 0x40
	s_add_u32 s50, s50, s100
	s_addc_u32 s51, s51, 0
	s_mov_b32 s94, 0
	s_add_i32 s4, s91, 0xb0
	s_cmp_gt_u32 s4, s3
	s_cselect_b32 s86, 1, 0
	s_or_b32 s86, s86, s84
	s_branch .Lat_loop

.Lat_diag_b:
	s_nop 7
	v_subrev_u32_e32 v234, 0, v223
	v_cmp_gt_i32_e64 s[4:5], 0, v234
	v_med3_i32 v234, v234, 0, s81
	v_lshl_add_u32 v234, v234, 2, s80
	ds_read_b32 v238, v234
	v_subrev_u32_e32 v235, 1, v223
	v_cmp_gt_i32_e64 s[6:7], 0, v235
	v_med3_i32 v235, v235, 0, s81
	v_lshl_add_u32 v235, v235, 2, s80
	ds_read_b32 v239, v235
	v_subrev_u32_e32 v236, 2, v223
	v_cmp_gt_i32_e64 s[8:9], 0, v236
	v_med3_i32 v236, v236, 0, s81
	v_lshl_add_u32 v236, v236, 2, s80
	ds_read_b32 v240, v236
	v_subrev_u32_e32 v237, 3, v223
	v_cmp_gt_i32_e64 s[10:11], 0, v237
	v_med3_i32 v237, v237, 0, s81
	v_lshl_add_u32 v237, v237, 2, s80
	ds_read_b32 v241, v237
	s_waitcnt lgkmcnt(0)
	v_add_f32_e32 v130, v130, v238
	v_cndmask_b32_e64 v130, v130, v216, s[4:5]
	v_add_f32_e32 v131, v131, v239
	v_cndmask_b32_e64 v131, v131, v216, s[6:7]
	v_add_f32_e32 v132, v132, v240
	v_cndmask_b32_e64 v132, v132, v216, s[8:9]
	v_add_f32_e32 v133, v133, v241
	v_cndmask_b32_e64 v133, v133, v216, s[10:11]
	v_subrev_u32_e32 v234, 16, v223
	v_cmp_gt_i32_e64 s[4:5], 0, v234
	v_med3_i32 v234, v234, 0, s81
	v_lshl_add_u32 v234, v234, 2, s80
	ds_read_b32 v238, v234
	v_subrev_u32_e32 v235, 17, v223
	v_cmp_gt_i32_e64 s[6:7], 0, v235
	v_med3_i32 v235, v235, 0, s81
	v_lshl_add_u32 v235, v235, 2, s80
	ds_read_b32 v239, v235
	v_subrev_u32_e32 v236, 18, v223
	v_cmp_gt_i32_e64 s[8:9], 0, v236
	v_med3_i32 v236, v236, 0, s81
	v_lshl_add_u32 v236, v236, 2, s80
	ds_read_b32 v240, v236
	v_subrev_u32_e32 v237, 19, v223
	v_cmp_gt_i32_e64 s[10:11], 0, v237
	v_med3_i32 v237, v237, 0, s81
	v_lshl_add_u32 v237, v237, 2, s80
	ds_read_b32 v241, v237
	s_waitcnt lgkmcnt(0)
	v_add_f32_e32 v134, v134, v238
	v_cndmask_b32_e64 v134, v134, v216, s[4:5]
	v_add_f32_e32 v135, v135, v239
	v_cndmask_b32_e64 v135, v135, v216, s[6:7]
	v_add_f32_e32 v136, v136, v240
	v_cndmask_b32_e64 v136, v136, v216, s[8:9]
	v_add_f32_e32 v137, v137, v241
	v_cndmask_b32_e64 v137, v137, v216, s[10:11]
	v_subrev_u32_e32 v234, 32, v223
	v_cmp_gt_i32_e64 s[4:5], 0, v234
	v_med3_i32 v234, v234, 0, s81
	v_lshl_add_u32 v234, v234, 2, s80
	ds_read_b32 v238, v234
	v_subrev_u32_e32 v235, 33, v223
	v_cmp_gt_i32_e64 s[6:7], 0, v235
	v_med3_i32 v235, v235, 0, s81
	v_lshl_add_u32 v235, v235, 2, s80
	ds_read_b32 v239, v235
	v_subrev_u32_e32 v236, 34, v223
	v_cmp_gt_i32_e64 s[8:9], 0, v236
	v_med3_i32 v236, v236, 0, s81
	v_lshl_add_u32 v236, v236, 2, s80
	ds_read_b32 v240, v236
	v_subrev_u32_e32 v237, 35, v223
	v_cmp_gt_i32_e64 s[10:11], 0, v237
	v_med3_i32 v237, v237, 0, s81
	v_lshl_add_u32 v237, v237, 2, s80
	ds_read_b32 v241, v237
	s_waitcnt lgkmcnt(0)
	v_add_f32_e32 v138, v138, v238
	v_cndmask_b32_e64 v138, v138, v216, s[4:5]
	v_add_f32_e32 v139, v139, v239
	v_cndmask_b32_e64 v139, v139, v216, s[6:7]
	v_add_f32_e32 v140, v140, v240
	v_cndmask_b32_e64 v140, v140, v216, s[8:9]
	v_add_f32_e32 v141, v141, v241
	v_cndmask_b32_e64 v141, v141, v216, s[10:11]
	v_subrev_u32_e32 v234, 48, v223
	v_cmp_gt_i32_e64 s[4:5], 0, v234
	v_med3_i32 v234, v234, 0, s81
	v_lshl_add_u32 v234, v234, 2, s80
	ds_read_b32 v238, v234
	v_subrev_u32_e32 v235, 49, v223
	v_cmp_gt_i32_e64 s[6:7], 0, v235
	v_med3_i32 v235, v235, 0, s81
	v_lshl_add_u32 v235, v235, 2, s80
	ds_read_b32 v239, v235
	v_subrev_u32_e32 v236, 50, v223
	v_cmp_gt_i32_e64 s[8:9], 0, v236
	v_med3_i32 v236, v236, 0, s81
	v_lshl_add_u32 v236, v236, 2, s80
	ds_read_b32 v240, v236
	v_subrev_u32_e32 v237, 51, v223
	v_cmp_gt_i32_e64 s[10:11], 0, v237
	v_med3_i32 v237, v237, 0, s81
	v_lshl_add_u32 v237, v237, 2, s80
	ds_read_b32 v241, v237
	s_waitcnt lgkmcnt(0)
	v_add_f32_e32 v142, v142, v238
	v_cndmask_b32_e64 v142, v142, v216, s[4:5]
	v_add_f32_e32 v143, v143, v239
	v_cndmask_b32_e64 v143, v143, v216, s[6:7]
	v_add_f32_e32 v144, v144, v240
	v_cndmask_b32_e64 v144, v144, v216, s[8:9]
	v_add_f32_e32 v145, v145, v241
	v_cndmask_b32_e64 v145, v145, v216, s[10:11]
	v_subrev_u32_e32 v234, -16, v223
	v_cmp_gt_i32_e64 s[4:5], 0, v234
	v_med3_i32 v234, v234, 0, s81
	v_lshl_add_u32 v234, v234, 2, s80
	ds_read_b32 v238, v234
	v_subrev_u32_e32 v235, -15, v223
	v_cmp_gt_i32_e64 s[6:7], 0, v235
	v_med3_i32 v235, v235, 0, s81
	v_lshl_add_u32 v235, v235, 2, s80
	ds_read_b32 v239, v235
	v_subrev_u32_e32 v236, -14, v223
	v_cmp_gt_i32_e64 s[8:9], 0, v236
	v_med3_i32 v236, v236, 0, s81
	v_lshl_add_u32 v236, v236, 2, s80
	ds_read_b32 v240, v236
	v_subrev_u32_e32 v237, -13, v223
	v_cmp_gt_i32_e64 s[10:11], 0, v237
	v_med3_i32 v237, v237, 0, s81
	v_lshl_add_u32 v237, v237, 2, s80
	ds_read_b32 v241, v237
	s_waitcnt lgkmcnt(0)
	v_add_f32_e32 v146, v146, v238
	v_cndmask_b32_e64 v146, v146, v216, s[4:5]
	v_add_f32_e32 v147, v147, v239
	v_cndmask_b32_e64 v147, v147, v216, s[6:7]
	v_add_f32_e32 v148, v148, v240
	v_cndmask_b32_e64 v148, v148, v216, s[8:9]
	v_add_f32_e32 v149, v149, v241
	v_cndmask_b32_e64 v149, v149, v216, s[10:11]
	v_subrev_u32_e32 v234, 0, v223
	v_cmp_gt_i32_e64 s[4:5], 0, v234
	v_med3_i32 v234, v234, 0, s81
	v_lshl_add_u32 v234, v234, 2, s80
	ds_read_b32 v238, v234
	v_subrev_u32_e32 v235, 1, v223
	v_cmp_gt_i32_e64 s[6:7], 0, v235
	v_med3_i32 v235, v235, 0, s81
	v_lshl_add_u32 v235, v235, 2, s80
	ds_read_b32 v239, v235
	v_subrev_u32_e32 v236, 2, v223
	v_cmp_gt_i32_e64 s[8:9], 0, v236
	v_med3_i32 v236, v236, 0, s81
	v_lshl_add_u32 v236, v236, 2, s80
	ds_read_b32 v240, v236
	v_subrev_u32_e32 v237, 3, v223
	v_cmp_gt_i32_e64 s[10:11], 0, v237
	v_med3_i32 v237, v237, 0, s81
	v_lshl_add_u32 v237, v237, 2, s80
	ds_read_b32 v241, v237
	s_waitcnt lgkmcnt(0)
	v_add_f32_e32 v150, v150, v238
	v_cndmask_b32_e64 v150, v150, v216, s[4:5]
	v_add_f32_e32 v151, v151, v239
	v_cndmask_b32_e64 v151, v151, v216, s[6:7]
	v_add_f32_e32 v152, v152, v240
	v_cndmask_b32_e64 v152, v152, v216, s[8:9]
	v_add_f32_e32 v153, v153, v241
	v_cndmask_b32_e64 v153, v153, v216, s[10:11]
	v_subrev_u32_e32 v234, 16, v223
	v_cmp_gt_i32_e64 s[4:5], 0, v234
	v_med3_i32 v234, v234, 0, s81
	v_lshl_add_u32 v234, v234, 2, s80
	ds_read_b32 v238, v234
	v_subrev_u32_e32 v235, 17, v223
	v_cmp_gt_i32_e64 s[6:7], 0, v235
	v_med3_i32 v235, v235, 0, s81
	v_lshl_add_u32 v235, v235, 2, s80
	ds_read_b32 v239, v235
	v_subrev_u32_e32 v236, 18, v223
	v_cmp_gt_i32_e64 s[8:9], 0, v236
	v_med3_i32 v236, v236, 0, s81
	v_lshl_add_u32 v236, v236, 2, s80
	ds_read_b32 v240, v236
	v_subrev_u32_e32 v237, 19, v223
	v_cmp_gt_i32_e64 s[10:11], 0, v237
	v_med3_i32 v237, v237, 0, s81
	v_lshl_add_u32 v237, v237, 2, s80
	ds_read_b32 v241, v237
	s_waitcnt lgkmcnt(0)
	v_add_f32_e32 v154, v154, v238
	v_cndmask_b32_e64 v154, v154, v216, s[4:5]
	v_add_f32_e32 v155, v155, v239
	v_cndmask_b32_e64 v155, v155, v216, s[6:7]
	v_add_f32_e32 v156, v156, v240
	v_cndmask_b32_e64 v156, v156, v216, s[8:9]
	v_add_f32_e32 v157, v157, v241
	v_cndmask_b32_e64 v157, v157, v216, s[10:11]
	v_subrev_u32_e32 v234, 32, v223
	v_cmp_gt_i32_e64 s[4:5], 0, v234
	v_med3_i32 v234, v234, 0, s81
	v_lshl_add_u32 v234, v234, 2, s80
	ds_read_b32 v238, v234
	v_subrev_u32_e32 v235, 33, v223
	v_cmp_gt_i32_e64 s[6:7], 0, v235
	v_med3_i32 v235, v235, 0, s81
	v_lshl_add_u32 v235, v235, 2, s80
	ds_read_b32 v239, v235
	v_subrev_u32_e32 v236, 34, v223
	v_cmp_gt_i32_e64 s[8:9], 0, v236
	v_med3_i32 v236, v236, 0, s81
	v_lshl_add_u32 v236, v236, 2, s80
	ds_read_b32 v240, v236
	v_subrev_u32_e32 v237, 35, v223
	v_cmp_gt_i32_e64 s[10:11], 0, v237
	v_med3_i32 v237, v237, 0, s81
	v_lshl_add_u32 v237, v237, 2, s80
	ds_read_b32 v241, v237
	s_waitcnt lgkmcnt(0)
	v_add_f32_e32 v158, v158, v238
	v_cndmask_b32_e64 v158, v158, v216, s[4:5]
	v_add_f32_e32 v159, v159, v239
	v_cndmask_b32_e64 v159, v159, v216, s[6:7]
	v_add_f32_e32 v160, v160, v240
	v_cndmask_b32_e64 v160, v160, v216, s[8:9]
	v_add_f32_e32 v161, v161, v241
	v_cndmask_b32_e64 v161, v161, v216, s[10:11]
	v_mov_b32_e32 v234, v221
	v_xor_b32_e32 v235, 64, v234
	v_xor_b32_e32 v236, 0x80, v234
	v_xor_b32_e32 v237, 0xc0, v234
	s_branch .Lat_sm_b
.Lat_sp_b:
	s_add_i32 s4, s91, 0xb0
	s_cmp_le_u32 s4, s3
	s_cbranch_scc0 .Lat_diag_b
